# s1 stagger 60x4 + accumulator zeroing with v_mov_b64 (64 instead of 128 VALU per tile) in 6 GEMM loops
# speedup vs baseline: 1.0034x; 1.0034x over previous
; #define PG8_NEXT(i, u) ((u).pm = __builtin_amdgcn_readlane(tab_pm, (i)), (u).pn = __builtin_amdgcn_readlane(tab_pn, (i)), (u).pm >= 0)
; template <class Epi, class Sched, bool ALIGN_EPI = true>
; __device__ __forceinline__ void gemm_phase(LAS unsigned char* lds, const Gemm g, const Sched& S, const Epi& E) {
;     ...
;         const bool has_next = PG8_NEXT(ui + 1, nxt);
;         const char* nA = has_next ? (const char*)g.A + (size_t)nxt.pm * tstep : cA; const char* nB = has_next ? (const char*)g.Bt + (size_t)nxt.pn * tstep : cB;
;     ...
;         if (!has_next) break;
; #pragma unroll
;         for (int a = 0; a < 2; ++a)
; #pragma unroll
;             for (int b = 0; b < 2; ++b)
; #pragma unroll
;                 for (int m = 0; m < 4; ++m)
; #pragma unroll
;                     for (int n = 0; n < 2; ++n) acc[a][b][m][n] = (f32x4){0.f, 0.f, 0.f, 0.f};
;         cur = nxt; cA = nA; cB = nB; ++ui;
.LBB0_194:
	s_add_i32 s80, s80, 1
	s_mov_b32 s81, s4
	v_readlane_b32 s4, v167, s80
	s_cmp_gt_i32 s4, -1
	s_mov_b64 s[36:37], s[10:11]
	s_cselect_b64 s[30:31], -1, 0
	s_lshl_b64 s[10:11], s[4:5], 20
	s_mov_b64 s[34:35], s[14:15]
	s_add_u32 s14, s29, s10
	s_addc_u32 s15, s40, s11
	s_mov_b32 s83, s8
	v_readlane_b32 s8, v141, s80
	s_and_b64 s[10:11], s[30:31], exec
	s_cselect_b32 s84, s15, s35
	s_cselect_b32 s85, s14, s34
	s_ashr_i32 s9, s8, 31
	s_lshl_b64 s[10:11], s[8:9], 20
	s_add_u32 s10, s41, s10
	s_addc_u32 s11, s43, s11
	s_and_b64 s[38:39], s[30:31], exec
	s_cselect_b32 s9, s11, s37
	s_cselect_b32 s86, s10, s36
	s_add_u32 s34, s34, 0x80080
	s_addc_u32 s35, s35, 0
	s_add_u32 s87, s36, 0x100
	v_mov_b32_e32 v0, 0
	s_addc_u32 s88, s37, 0
	s_mov_b32 s89, -2
	v_mov_b32_e32 v1, v0
	v_mov_b64_e32 v[2:3], v[0:1]
	v_mov_b64_e32 v[4:5], v[0:1]
	v_mov_b64_e32 v[6:7], v[0:1]
	v_mov_b64_e32 v[8:9], v[0:1]
	v_mov_b64_e32 v[10:11], v[0:1]
	v_mov_b64_e32 v[12:13], v[0:1]
	v_mov_b64_e32 v[14:15], v[0:1]
	v_mov_b64_e32 v[16:17], v[0:1]
	v_mov_b64_e32 v[18:19], v[0:1]
	v_mov_b64_e32 v[20:21], v[0:1]
	v_mov_b64_e32 v[22:23], v[0:1]
	v_mov_b64_e32 v[24:25], v[0:1]
	v_mov_b64_e32 v[26:27], v[0:1]
	v_mov_b64_e32 v[28:29], v[0:1]
	v_mov_b64_e32 v[30:31], v[0:1]
	v_mov_b64_e32 v[32:33], v[0:1]
	v_mov_b64_e32 v[34:35], v[0:1]
	v_mov_b64_e32 v[36:37], v[0:1]
	v_mov_b64_e32 v[38:39], v[0:1]
	v_mov_b64_e32 v[40:41], v[0:1]
	v_mov_b64_e32 v[42:43], v[0:1]
	v_mov_b64_e32 v[44:45], v[0:1]
	v_mov_b64_e32 v[46:47], v[0:1]
	v_mov_b64_e32 v[48:49], v[0:1]
	v_mov_b64_e32 v[50:51], v[0:1]
	v_mov_b64_e32 v[52:53], v[0:1]
	v_mov_b64_e32 v[54:55], v[0:1]
	v_mov_b64_e32 v[56:57], v[0:1]
	v_mov_b64_e32 v[58:59], v[0:1]
	v_mov_b64_e32 v[60:61], v[0:1]
	v_mov_b64_e32 v[62:63], v[0:1]
	v_mov_b64_e32 v[64:65], v[0:1]
	v_mov_b64_e32 v[66:67], v[0:1]
	v_mov_b64_e32 v[68:69], v[0:1]
	v_mov_b64_e32 v[70:71], v[0:1]
	v_mov_b64_e32 v[72:73], v[0:1]
	v_mov_b64_e32 v[74:75], v[0:1]
	v_mov_b64_e32 v[76:77], v[0:1]
	v_mov_b64_e32 v[78:79], v[0:1]
	v_mov_b64_e32 v[80:81], v[0:1]
	v_mov_b64_e32 v[82:83], v[0:1]
	v_mov_b64_e32 v[84:85], v[0:1]
	v_mov_b64_e32 v[86:87], v[0:1]
	v_mov_b64_e32 v[88:89], v[0:1]
	v_mov_b64_e32 v[90:91], v[0:1]
	v_mov_b64_e32 v[92:93], v[0:1]
	v_mov_b64_e32 v[94:95], v[0:1]
	v_mov_b64_e32 v[96:97], v[0:1]
	v_mov_b64_e32 v[98:99], v[0:1]
	v_mov_b64_e32 v[100:101], v[0:1]
	v_mov_b64_e32 v[102:103], v[0:1]
	v_mov_b64_e32 v[104:105], v[0:1]
	v_mov_b64_e32 v[106:107], v[0:1]
	v_mov_b64_e32 v[108:109], v[0:1]
	v_mov_b64_e32 v[110:111], v[0:1]
	v_mov_b64_e32 v[112:113], v[0:1]
	v_mov_b64_e32 v[114:115], v[0:1]
	v_mov_b64_e32 v[116:117], v[0:1]
	v_mov_b64_e32 v[118:119], v[0:1]
	v_mov_b64_e32 v[120:121], v[0:1]
	v_mov_b64_e32 v[122:123], v[0:1]
	v_mov_b64_e32 v[124:125], v[0:1]
	v_mov_b64_e32 v[126:127], v[0:1]

; #define PG8_NEXT(i, u) ((u).pm = __builtin_amdgcn_readlane(tab_pm, (i)), (u).pn = __builtin_amdgcn_readlane(tab_pn, (i)), (u).pm >= 0)
; template <class Epi, class Sched, bool ALIGN_EPI = true>
; __device__ __forceinline__ void gemm_phase(LAS unsigned char* lds, const Gemm g, const Sched& S, const Epi& E) {
;     ...
;         const bool has_next = PG8_NEXT(ui + 1, nxt);
;         const char* nA = has_next ? (const char*)g.A + (size_t)nxt.pm * tstep : cA; const char* nB = has_next ? (const char*)g.Bt + (size_t)nxt.pn * tstep : cB;
;     ...
;         if (!has_next) break;
; #pragma unroll
;         for (int a = 0; a < 2; ++a)
; #pragma unroll
;             for (int b = 0; b < 2; ++b)
; #pragma unroll
;                 for (int m = 0; m < 4; ++m)
; #pragma unroll
;                     for (int n = 0; n < 2; ++n) acc[a][b][m][n] = (f32x4){0.f, 0.f, 0.f, 0.f};
;         cur = nxt; cA = nA; cB = nB; ++ui;
.LBB0_222:
	s_add_i32 s93, s93, 1
	s_mov_b32 s95, s8
	v_readlane_b32 s8, v157, s93
	s_cmp_gt_i32 s8, -1
	s_mov_b32 s9, s31
	s_mov_b64 s[78:79], s[14:15]
	s_cselect_b64 s[58:59], -1, 0
	s_lshl_b64 s[14:15], s[8:9], 20
	s_mov_b64 s[76:77], s[20:21]
	s_add_u32 s20, s41, s14
	s_addc_u32 s21, s43, s15
	s_mov_b32 s94, s10
	v_readlane_b32 s10, v155, s93
	s_and_b64 s[14:15], s[58:59], exec
	s_cselect_b32 s9, s21, s77
	s_cselect_b32 s30, s20, s76
	s_ashr_i32 s11, s10, 31
	s_lshl_b64 s[14:15], s[10:11], 20
	s_add_u32 s14, s3, s14
	s_addc_u32 s15, s37, s15
	s_and_b64 s[80:81], s[58:59], exec
	s_cselect_b32 s11, s15, s79
	s_cselect_b32 s96, s14, s78
	s_add_u32 s76, s76, 0x80080
	s_addc_u32 s77, s77, 0
	s_add_u32 s97, s78, 0x100
	v_mov_b32_e32 v0, 0
	s_addc_u32 vcc_lo, s79, 0
	s_mov_b32 vcc_hi, -2
	v_mov_b32_e32 v1, v0
	v_mov_b64_e32 v[2:3], v[0:1]
	v_mov_b64_e32 v[4:5], v[0:1]
	v_mov_b64_e32 v[6:7], v[0:1]
	v_mov_b64_e32 v[8:9], v[0:1]
	v_mov_b64_e32 v[10:11], v[0:1]
	v_mov_b64_e32 v[12:13], v[0:1]
	v_mov_b64_e32 v[14:15], v[0:1]
	v_mov_b64_e32 v[16:17], v[0:1]
	v_mov_b64_e32 v[18:19], v[0:1]
	v_mov_b64_e32 v[20:21], v[0:1]
	v_mov_b64_e32 v[22:23], v[0:1]
	v_mov_b64_e32 v[24:25], v[0:1]
	v_mov_b64_e32 v[26:27], v[0:1]
	v_mov_b64_e32 v[28:29], v[0:1]
	v_mov_b64_e32 v[30:31], v[0:1]
	v_mov_b64_e32 v[32:33], v[0:1]
	v_mov_b64_e32 v[34:35], v[0:1]
	v_mov_b64_e32 v[36:37], v[0:1]
	v_mov_b64_e32 v[38:39], v[0:1]
	v_mov_b64_e32 v[40:41], v[0:1]
	v_mov_b64_e32 v[42:43], v[0:1]
	v_mov_b64_e32 v[44:45], v[0:1]
	v_mov_b64_e32 v[46:47], v[0:1]
	v_mov_b64_e32 v[48:49], v[0:1]
	v_mov_b64_e32 v[50:51], v[0:1]
	v_mov_b64_e32 v[52:53], v[0:1]
	v_mov_b64_e32 v[54:55], v[0:1]
	v_mov_b64_e32 v[56:57], v[0:1]
	v_mov_b64_e32 v[58:59], v[0:1]
	v_mov_b64_e32 v[60:61], v[0:1]
	v_mov_b64_e32 v[62:63], v[0:1]
	v_mov_b64_e32 v[64:65], v[0:1]
	v_mov_b64_e32 v[66:67], v[0:1]
	v_mov_b64_e32 v[68:69], v[0:1]
	v_mov_b64_e32 v[70:71], v[0:1]
	v_mov_b64_e32 v[72:73], v[0:1]
	v_mov_b64_e32 v[74:75], v[0:1]
	v_mov_b64_e32 v[76:77], v[0:1]
	v_mov_b64_e32 v[78:79], v[0:1]
	v_mov_b64_e32 v[80:81], v[0:1]
	v_mov_b64_e32 v[82:83], v[0:1]
	v_mov_b64_e32 v[84:85], v[0:1]
	v_mov_b64_e32 v[86:87], v[0:1]
	v_mov_b64_e32 v[88:89], v[0:1]
	v_mov_b64_e32 v[90:91], v[0:1]
	v_mov_b64_e32 v[92:93], v[0:1]
	v_mov_b64_e32 v[94:95], v[0:1]
	v_mov_b64_e32 v[96:97], v[0:1]
	v_mov_b64_e32 v[98:99], v[0:1]
	v_mov_b64_e32 v[100:101], v[0:1]
	v_mov_b64_e32 v[102:103], v[0:1]
	v_mov_b64_e32 v[104:105], v[0:1]
	v_mov_b64_e32 v[106:107], v[0:1]
	v_mov_b64_e32 v[108:109], v[0:1]
	v_mov_b64_e32 v[110:111], v[0:1]
	v_mov_b64_e32 v[112:113], v[0:1]
	v_mov_b64_e32 v[114:115], v[0:1]
	v_mov_b64_e32 v[116:117], v[0:1]
	v_mov_b64_e32 v[118:119], v[0:1]
	v_mov_b64_e32 v[120:121], v[0:1]
	v_mov_b64_e32 v[122:123], v[0:1]
	v_mov_b64_e32 v[124:125], v[0:1]
	v_mov_b64_e32 v[126:127], v[0:1]

; #define PG8_NEXT(i, u) ((u).pm = __builtin_amdgcn_readlane(tab_pm, (i)), (u).pn = __builtin_amdgcn_readlane(tab_pn, (i)), (u).pm >= 0)
; template <class Epi, class Sched, bool ALIGN_EPI = true>
; __device__ __forceinline__ void gemm_phase(LAS unsigned char* lds, const Gemm g, const Sched& S, const Epi& E) {
;     ...
;         const bool has_next = PG8_NEXT(ui + 1, nxt);
;         const char* nA = has_next ? (const char*)g.A + (size_t)nxt.pm * tstep : cA; const char* nB = has_next ? (const char*)g.Bt + (size_t)nxt.pn * tstep : cB;
;     ...
;         if (!has_next) break;
; #pragma unroll
;         for (int a = 0; a < 2; ++a)
; #pragma unroll
;             for (int b = 0; b < 2; ++b)
; #pragma unroll
;                 for (int m = 0; m < 4; ++m)
; #pragma unroll
;                     for (int n = 0; n < 2; ++n) acc[a][b][m][n] = (f32x4){0.f, 0.f, 0.f, 0.f};
;         cur = nxt; cA = nA; cB = nB; ++ui;
.LBB0_559:
	s_add_i32 s50, s50, 1
	s_mov_b32 s52, s6
	v_readlane_b32 s6, v201, s50
	s_cmp_gt_i32 s6, -1
	s_mov_b64 s[28:29], s[10:11]
	s_cselect_b64 s[24:25], -1, 0
	s_lshl_b64 s[10:11], s[6:7], 20
	s_mov_b64 s[26:27], s[12:13]
	s_add_u32 s12, s3, s10
	s_addc_u32 s13, s34, s11
	s_mov_b32 s51, s8
	v_readlane_b32 s8, v200, s50
	s_and_b64 s[10:11], s[24:25], exec
	s_cselect_b32 s53, s13, s27
	s_cselect_b32 s54, s12, s26
	s_ashr_i32 s9, s8, 31
	s_lshl_b64 s[10:11], s[8:9], 20
	s_add_u32 s10, s35, s10
	s_addc_u32 s11, s36, s11
	s_and_b64 s[30:31], s[24:25], exec
	s_cselect_b32 s9, s11, s29
	s_cselect_b32 s55, s10, s28
	s_add_u32 s26, s26, 0x80080
	s_addc_u32 s27, s27, 0
	s_add_u32 s56, s28, 0x100
	v_mov_b32_e32 v0, 0
	s_addc_u32 s57, s29, 0
	s_mov_b32 s58, -2
	s_waitcnt lgkmcnt(0)
	v_mov_b32_e32 v1, v0
	v_mov_b64_e32 v[2:3], v[0:1]
	v_mov_b64_e32 v[4:5], v[0:1]
	v_mov_b64_e32 v[6:7], v[0:1]
	v_mov_b64_e32 v[8:9], v[0:1]
	v_mov_b64_e32 v[10:11], v[0:1]
	v_mov_b64_e32 v[12:13], v[0:1]
	v_mov_b64_e32 v[14:15], v[0:1]
	v_mov_b64_e32 v[16:17], v[0:1]
	v_mov_b64_e32 v[18:19], v[0:1]
	v_mov_b64_e32 v[20:21], v[0:1]
	v_mov_b64_e32 v[22:23], v[0:1]
	v_mov_b64_e32 v[24:25], v[0:1]
	v_mov_b64_e32 v[26:27], v[0:1]
	v_mov_b64_e32 v[28:29], v[0:1]
	v_mov_b64_e32 v[30:31], v[0:1]
	v_mov_b64_e32 v[32:33], v[0:1]
	v_mov_b64_e32 v[34:35], v[0:1]
	v_mov_b64_e32 v[36:37], v[0:1]
	v_mov_b64_e32 v[38:39], v[0:1]
	v_mov_b64_e32 v[40:41], v[0:1]
	v_mov_b64_e32 v[42:43], v[0:1]
	v_mov_b64_e32 v[44:45], v[0:1]
	v_mov_b64_e32 v[46:47], v[0:1]
	v_mov_b64_e32 v[48:49], v[0:1]
	v_mov_b64_e32 v[50:51], v[0:1]
	v_mov_b64_e32 v[52:53], v[0:1]
	v_mov_b64_e32 v[54:55], v[0:1]
	v_mov_b64_e32 v[56:57], v[0:1]
	v_mov_b64_e32 v[58:59], v[0:1]
	v_mov_b64_e32 v[60:61], v[0:1]
	v_mov_b64_e32 v[62:63], v[0:1]
	v_mov_b64_e32 v[64:65], v[0:1]
	v_mov_b64_e32 v[66:67], v[0:1]
	v_mov_b64_e32 v[68:69], v[0:1]
	v_mov_b64_e32 v[70:71], v[0:1]
	v_mov_b64_e32 v[72:73], v[0:1]
	v_mov_b64_e32 v[74:75], v[0:1]
	v_mov_b64_e32 v[76:77], v[0:1]
	v_mov_b64_e32 v[78:79], v[0:1]
	v_mov_b64_e32 v[80:81], v[0:1]
	v_mov_b64_e32 v[82:83], v[0:1]
	v_mov_b64_e32 v[84:85], v[0:1]
	v_mov_b64_e32 v[86:87], v[0:1]
	v_mov_b64_e32 v[88:89], v[0:1]
	v_mov_b64_e32 v[90:91], v[0:1]
	v_mov_b64_e32 v[92:93], v[0:1]
	v_mov_b64_e32 v[94:95], v[0:1]
	v_mov_b64_e32 v[96:97], v[0:1]
	v_mov_b64_e32 v[98:99], v[0:1]
	v_mov_b64_e32 v[100:101], v[0:1]
	v_mov_b64_e32 v[102:103], v[0:1]
	v_mov_b64_e32 v[104:105], v[0:1]
	v_mov_b64_e32 v[106:107], v[0:1]
	v_mov_b64_e32 v[108:109], v[0:1]
	v_mov_b64_e32 v[110:111], v[0:1]
	v_mov_b64_e32 v[112:113], v[0:1]
	v_mov_b64_e32 v[114:115], v[0:1]
	v_mov_b64_e32 v[116:117], v[0:1]
	v_mov_b64_e32 v[118:119], v[0:1]
	v_mov_b64_e32 v[120:121], v[0:1]
	v_mov_b64_e32 v[122:123], v[0:1]
	v_mov_b64_e32 v[124:125], v[0:1]
	v_mov_b64_e32 v[126:127], v[0:1]

; #define PG8_NEXT(i, u) ((u).pm = __builtin_amdgcn_readlane(tab_pm, (i)), (u).pn = __builtin_amdgcn_readlane(tab_pn, (i)), (u).pm >= 0)
; template <class Epi, class Sched, bool ALIGN_EPI = true>
; __device__ __forceinline__ void gemm_phase(LAS unsigned char* lds, const Gemm g, const Sched& S, const Epi& E) {
;     ...
;         const bool has_next = PG8_NEXT(ui + 1, nxt);
;         const char* nA = has_next ? (const char*)g.A + (size_t)nxt.pm * tstep : cA; const char* nB = has_next ? (const char*)g.Bt + (size_t)nxt.pn * tstep : cB;
;     ...
;         if (!has_next) break;
; #pragma unroll
;         for (int a = 0; a < 2; ++a)
; #pragma unroll
;             for (int b = 0; b < 2; ++b)
; #pragma unroll
;                 for (int m = 0; m < 4; ++m)
; #pragma unroll
;                     for (int n = 0; n < 2; ++n) acc[a][b][m][n] = (f32x4){0.f, 0.f, 0.f, 0.f};
;         cur = nxt; cA = nA; cB = nB; ++ui;
.LBB0_646:
	s_add_i32 s48, s48, 1
	s_mov_b32 s50, s4
	v_readlane_b32 s4, v143, s48
	s_cmp_gt_i32 s4, -1
	s_mov_b64 s[26:27], s[8:9]
	s_cselect_b64 s[22:23], -1, 0
	s_lshl_b64 s[8:9], s[4:5], 20
	s_mov_b64 s[24:25], s[10:11]
	s_add_u32 s10, s30, s8
	s_addc_u32 s11, s31, s9
	s_mov_b32 s49, s6
	v_readlane_b32 s6, v142, s48
	s_and_b64 s[8:9], s[22:23], exec
	s_cselect_b32 s51, s11, s25
	s_cselect_b32 s52, s10, s24
	s_ashr_i32 s7, s6, 31
	s_lshl_b64 s[8:9], s[6:7], 20
	s_add_u32 s8, s34, s8
	s_addc_u32 s9, s35, s9
	s_and_b64 s[28:29], s[22:23], exec
	s_cselect_b32 s7, s9, s27
	s_cselect_b32 s53, s8, s26
	s_add_u32 s24, s24, 0x80080
	s_addc_u32 s25, s25, 0
	s_add_u32 s54, s26, 0x100
	v_mov_b32_e32 v0, 0
	s_addc_u32 s55, s27, 0
	s_mov_b32 s56, -2
	v_mov_b32_e32 v1, v0
	v_mov_b64_e32 v[2:3], v[0:1]
	v_mov_b64_e32 v[4:5], v[0:1]
	v_mov_b64_e32 v[6:7], v[0:1]
	v_mov_b64_e32 v[8:9], v[0:1]
	v_mov_b64_e32 v[10:11], v[0:1]
	v_mov_b64_e32 v[12:13], v[0:1]
	v_mov_b64_e32 v[14:15], v[0:1]
	v_mov_b64_e32 v[16:17], v[0:1]
	v_mov_b64_e32 v[18:19], v[0:1]
	v_mov_b64_e32 v[20:21], v[0:1]
	v_mov_b64_e32 v[22:23], v[0:1]
	v_mov_b64_e32 v[24:25], v[0:1]
	v_mov_b64_e32 v[26:27], v[0:1]
	v_mov_b64_e32 v[28:29], v[0:1]
	v_mov_b64_e32 v[30:31], v[0:1]
	v_mov_b64_e32 v[32:33], v[0:1]
	v_mov_b64_e32 v[34:35], v[0:1]
	v_mov_b64_e32 v[36:37], v[0:1]
	v_mov_b64_e32 v[38:39], v[0:1]
	v_mov_b64_e32 v[40:41], v[0:1]
	v_mov_b64_e32 v[42:43], v[0:1]
	v_mov_b64_e32 v[44:45], v[0:1]
	v_mov_b64_e32 v[46:47], v[0:1]
	v_mov_b64_e32 v[48:49], v[0:1]
	v_mov_b64_e32 v[50:51], v[0:1]
	v_mov_b64_e32 v[52:53], v[0:1]
	v_mov_b64_e32 v[54:55], v[0:1]
	v_mov_b64_e32 v[56:57], v[0:1]
	v_mov_b64_e32 v[58:59], v[0:1]
	v_mov_b64_e32 v[60:61], v[0:1]
	v_mov_b64_e32 v[62:63], v[0:1]
	v_mov_b64_e32 v[64:65], v[0:1]
	v_mov_b64_e32 v[66:67], v[0:1]
	v_mov_b64_e32 v[68:69], v[0:1]
	v_mov_b64_e32 v[70:71], v[0:1]
	v_mov_b64_e32 v[72:73], v[0:1]
	v_mov_b64_e32 v[74:75], v[0:1]
	v_mov_b64_e32 v[76:77], v[0:1]
	v_mov_b64_e32 v[78:79], v[0:1]
	v_mov_b64_e32 v[80:81], v[0:1]
	v_mov_b64_e32 v[82:83], v[0:1]
	v_mov_b64_e32 v[84:85], v[0:1]
	v_mov_b64_e32 v[86:87], v[0:1]
	v_mov_b64_e32 v[88:89], v[0:1]
	v_mov_b64_e32 v[90:91], v[0:1]
	v_mov_b64_e32 v[92:93], v[0:1]
	v_mov_b64_e32 v[94:95], v[0:1]
	v_mov_b64_e32 v[96:97], v[0:1]
	v_mov_b64_e32 v[98:99], v[0:1]
	v_mov_b64_e32 v[100:101], v[0:1]
	v_mov_b64_e32 v[102:103], v[0:1]
	v_mov_b64_e32 v[104:105], v[0:1]
	v_mov_b64_e32 v[106:107], v[0:1]
	v_mov_b64_e32 v[108:109], v[0:1]
	v_mov_b64_e32 v[110:111], v[0:1]
	v_mov_b64_e32 v[112:113], v[0:1]
	v_mov_b64_e32 v[114:115], v[0:1]
	v_mov_b64_e32 v[116:117], v[0:1]
	v_mov_b64_e32 v[118:119], v[0:1]
	v_mov_b64_e32 v[120:121], v[0:1]
	v_mov_b64_e32 v[122:123], v[0:1]
	v_mov_b64_e32 v[124:125], v[0:1]
	v_mov_b64_e32 v[126:127], v[0:1]

; template <class Epi, class Sched, bool ALIGN_EPI = true>
; __device__ __forceinline__ void gemm_phase(LAS unsigned char* lds, const Gemm g, const Sched& S, const Epi& E) {
;     ...
; #pragma unroll
;         for (int a = 0; a < 2; ++a)
; #pragma unroll
;             for (int b = 0; b < 2; ++b)
; #pragma unroll
;                 for (int m = 0; m < 4; ++m)
; #pragma unroll
;                     for (int n = 0; n < 2; ++n) acc[a][b][m][n] = (f32x4){0.f, 0.f, 0.f, 0.f};
;         cur = nxt; cA = nA; cB = nB; ++ui;
.LBB0_745:
	s_add_u32 s54, s24, 0x100
	v_mov_b32_e32 v0, 0
	s_addc_u32 s55, s25, 0
	s_mov_b32 s56, -2
	s_waitcnt lgkmcnt(0)
	v_mov_b32_e32 v1, v0
	v_mov_b64_e32 v[2:3], v[0:1]
	v_mov_b64_e32 v[4:5], v[0:1]
	v_mov_b64_e32 v[6:7], v[0:1]
	v_mov_b64_e32 v[8:9], v[0:1]
	v_mov_b64_e32 v[10:11], v[0:1]
	v_mov_b64_e32 v[12:13], v[0:1]
	v_mov_b64_e32 v[14:15], v[0:1]
	v_mov_b64_e32 v[16:17], v[0:1]
	v_mov_b64_e32 v[18:19], v[0:1]
	v_mov_b64_e32 v[20:21], v[0:1]
	v_mov_b64_e32 v[22:23], v[0:1]
	v_mov_b64_e32 v[24:25], v[0:1]
	v_mov_b64_e32 v[26:27], v[0:1]
	v_mov_b64_e32 v[28:29], v[0:1]
	v_mov_b64_e32 v[30:31], v[0:1]
	v_mov_b64_e32 v[32:33], v[0:1]
	v_mov_b64_e32 v[34:35], v[0:1]
	v_mov_b64_e32 v[36:37], v[0:1]
	v_mov_b64_e32 v[38:39], v[0:1]
	v_mov_b64_e32 v[40:41], v[0:1]
	v_mov_b64_e32 v[42:43], v[0:1]
	v_mov_b64_e32 v[44:45], v[0:1]
	v_mov_b64_e32 v[46:47], v[0:1]
	v_mov_b64_e32 v[48:49], v[0:1]
	v_mov_b64_e32 v[50:51], v[0:1]
	v_mov_b64_e32 v[52:53], v[0:1]
	v_mov_b64_e32 v[54:55], v[0:1]
	v_mov_b64_e32 v[56:57], v[0:1]
	v_mov_b64_e32 v[58:59], v[0:1]
	v_mov_b64_e32 v[60:61], v[0:1]
	v_mov_b64_e32 v[62:63], v[0:1]
	v_mov_b64_e32 v[64:65], v[0:1]
	v_mov_b64_e32 v[66:67], v[0:1]
	v_mov_b64_e32 v[68:69], v[0:1]
	v_mov_b64_e32 v[70:71], v[0:1]
	v_mov_b64_e32 v[72:73], v[0:1]
	v_mov_b64_e32 v[74:75], v[0:1]
	v_mov_b64_e32 v[76:77], v[0:1]
	v_mov_b64_e32 v[78:79], v[0:1]
	v_mov_b64_e32 v[80:81], v[0:1]
	v_mov_b64_e32 v[82:83], v[0:1]
	v_mov_b64_e32 v[84:85], v[0:1]
	v_mov_b64_e32 v[86:87], v[0:1]
	v_mov_b64_e32 v[88:89], v[0:1]
	v_mov_b64_e32 v[90:91], v[0:1]
	v_mov_b64_e32 v[92:93], v[0:1]
	v_mov_b64_e32 v[94:95], v[0:1]
	v_mov_b64_e32 v[96:97], v[0:1]
	v_mov_b64_e32 v[98:99], v[0:1]
	v_mov_b64_e32 v[100:101], v[0:1]
	v_mov_b64_e32 v[102:103], v[0:1]
	v_mov_b64_e32 v[104:105], v[0:1]
	v_mov_b64_e32 v[106:107], v[0:1]
	v_mov_b64_e32 v[108:109], v[0:1]
	v_mov_b64_e32 v[110:111], v[0:1]
	v_mov_b64_e32 v[112:113], v[0:1]
	v_mov_b64_e32 v[114:115], v[0:1]
	v_mov_b64_e32 v[116:117], v[0:1]
	v_mov_b64_e32 v[118:119], v[0:1]
	v_mov_b64_e32 v[120:121], v[0:1]
	v_mov_b64_e32 v[122:123], v[0:1]
	v_mov_b64_e32 v[124:125], v[0:1]
	v_mov_b64_e32 v[126:127], v[0:1]

; #define PG8_NEXT(i, u) ((u).pm = __builtin_amdgcn_readlane(tab_pm, (i)), (u).pn = __builtin_amdgcn_readlane(tab_pn, (i)), (u).pm >= 0)
; template <class Epi, class Sched, bool ALIGN_EPI = true>
; __device__ __forceinline__ void gemm_phase(LAS unsigned char* lds, const Gemm g, const Sched& S, const Epi& E) {
;     ...
;         const bool has_next = PG8_NEXT(ui + 1, nxt);
;         const char* nA = has_next ? (const char*)g.A + (size_t)nxt.pm * tstep : cA; const char* nB = has_next ? (const char*)g.Bt + (size_t)nxt.pn * tstep : cB;
;     ...
;         if (!has_next) break;
; #pragma unroll
;         for (int a = 0; a < 2; ++a)
; #pragma unroll
;             for (int b = 0; b < 2; ++b)
; #pragma unroll
;                 for (int m = 0; m < 4; ++m)
; #pragma unroll
;                     for (int n = 0; n < 2; ++n) acc[a][b][m][n] = (f32x4){0.f, 0.f, 0.f, 0.f};
;         cur = nxt; cA = nA; cB = nB; ++ui;
.LBB0_836:
	s_add_i32 s52, s52, 1
	s_mov_b32 s54, s6
	v_readlane_b32 s6, v204, s52
	s_cmp_gt_i32 s6, -1
	s_mov_b64 s[36:37], s[12:13]
	s_cselect_b64 s[30:31], -1, 0
	s_lshl_b64 s[12:13], s[6:7], 20
	s_mov_b64 s[34:35], s[14:15]
	s_add_u32 s14, s8, s12
	s_addc_u32 s15, s9, s13
	s_mov_b32 s53, s10
	v_readlane_b32 s10, v203, s52
	s_and_b64 s[12:13], s[30:31], exec
	s_cselect_b32 s55, s15, s35
	s_cselect_b32 s56, s14, s34
	s_ashr_i32 s11, s10, 31
	s_lshl_b64 s[12:13], s[10:11], 20
	s_add_u32 s12, s3, s12
	s_addc_u32 s13, s40, s13
	s_and_b64 s[38:39], s[30:31], exec
	s_cselect_b32 s11, s13, s37
	s_cselect_b32 s57, s12, s36
	s_add_u32 s34, s34, 0x80080
	s_addc_u32 s35, s35, 0
	s_add_u32 s58, s36, 0x100
	v_mov_b32_e32 v0, 0
	s_addc_u32 s59, s37, 0
	s_mov_b32 s60, -2
	s_waitcnt lgkmcnt(0)
	v_mov_b32_e32 v1, v0
	v_mov_b64_e32 v[2:3], v[0:1]
	v_mov_b64_e32 v[4:5], v[0:1]
	v_mov_b64_e32 v[6:7], v[0:1]
	v_mov_b64_e32 v[8:9], v[0:1]
	v_mov_b64_e32 v[10:11], v[0:1]
	v_mov_b64_e32 v[12:13], v[0:1]
	v_mov_b64_e32 v[14:15], v[0:1]
	v_mov_b64_e32 v[16:17], v[0:1]
	v_mov_b64_e32 v[18:19], v[0:1]
	v_mov_b64_e32 v[20:21], v[0:1]
	v_mov_b64_e32 v[22:23], v[0:1]
	v_mov_b64_e32 v[24:25], v[0:1]
	v_mov_b64_e32 v[26:27], v[0:1]
	v_mov_b64_e32 v[28:29], v[0:1]
	v_mov_b64_e32 v[30:31], v[0:1]
	v_mov_b64_e32 v[32:33], v[0:1]
	v_mov_b64_e32 v[34:35], v[0:1]
	v_mov_b64_e32 v[36:37], v[0:1]
	v_mov_b64_e32 v[38:39], v[0:1]
	v_mov_b64_e32 v[40:41], v[0:1]
	v_mov_b64_e32 v[42:43], v[0:1]
	v_mov_b64_e32 v[44:45], v[0:1]
	v_mov_b64_e32 v[46:47], v[0:1]
	v_mov_b64_e32 v[48:49], v[0:1]
	v_mov_b64_e32 v[50:51], v[0:1]
	v_mov_b64_e32 v[52:53], v[0:1]
	v_mov_b64_e32 v[54:55], v[0:1]
	v_mov_b64_e32 v[56:57], v[0:1]
	v_mov_b64_e32 v[58:59], v[0:1]
	v_mov_b64_e32 v[60:61], v[0:1]
	v_mov_b64_e32 v[62:63], v[0:1]
	v_mov_b64_e32 v[64:65], v[0:1]
	v_mov_b64_e32 v[66:67], v[0:1]
	v_mov_b64_e32 v[68:69], v[0:1]
	v_mov_b64_e32 v[70:71], v[0:1]
	v_mov_b64_e32 v[72:73], v[0:1]
	v_mov_b64_e32 v[74:75], v[0:1]
	v_mov_b64_e32 v[76:77], v[0:1]
	v_mov_b64_e32 v[78:79], v[0:1]
	v_mov_b64_e32 v[80:81], v[0:1]
	v_mov_b64_e32 v[82:83], v[0:1]
	v_mov_b64_e32 v[84:85], v[0:1]
	v_mov_b64_e32 v[86:87], v[0:1]
	v_mov_b64_e32 v[88:89], v[0:1]
	v_mov_b64_e32 v[90:91], v[0:1]
	v_mov_b64_e32 v[92:93], v[0:1]
	v_mov_b64_e32 v[94:95], v[0:1]
	v_mov_b64_e32 v[96:97], v[0:1]
	v_mov_b64_e32 v[98:99], v[0:1]
	v_mov_b64_e32 v[100:101], v[0:1]
	v_mov_b64_e32 v[102:103], v[0:1]
	v_mov_b64_e32 v[104:105], v[0:1]
	v_mov_b64_e32 v[106:107], v[0:1]
	v_mov_b64_e32 v[108:109], v[0:1]
	v_mov_b64_e32 v[110:111], v[0:1]
	v_mov_b64_e32 v[112:113], v[0:1]
	v_mov_b64_e32 v[114:115], v[0:1]
	v_mov_b64_e32 v[116:117], v[0:1]
	v_mov_b64_e32 v[118:119], v[0:1]
	v_mov_b64_e32 v[128:129], v[0:1]
	v_mov_b64_e32 v[130:131], v[0:1]
	v_mov_b64_e32 v[140:141], v[0:1]
	v_mov_b64_e32 v[142:143], v[0:1]
